# ffn-in tile order: co-resident workgroups (b, b+256) get the same weight tile, adjacent row tiles
# baseline (speedup 1.0000x reference)
.LBB0_192:
	v_mov_b32_e32 v0, v1
	s_mul_hi_i32 s23, s22, 0x2e8ba2e9
	v_mbcnt_lo_u32_b32 v0, -1, v0
	v_mbcnt_hi_u32_b32 v0, -1, v0
	s_lshr_b32 s24, s23, 31
	s_ashr_i32 s23, s23, 3
	v_add_u32_e32 v90, s80, v0
	s_add_i32 s23, s23, s24
	s_mov_b32 s98, s23
	s_mul_i32 s24, s98, 44
	s_sub_i32 s25, s22, s24
	s_cmpk_eq_u32 s81, 0x200
	s_cbranch_scc0 .Lffp_nomap
	s_lshr_b32 s24, s22, 8
	s_and_b32 s25, s22, 0xff
	s_cmpk_lt_u32 s24, 4
	s_cbranch_scc0 .Lffp_r2
	s_and_b32 s98, s24, 1
	s_lshr_b32 s24, s24, 1
	s_lshl_b32 s24, s24, 8
	s_add_u32 s25, s25, s24
	s_branch .Lffp_jh
.Lffp_r2:
	s_cmpk_eq_u32 s24, 5
	s_cbranch_scc1 .Lffp_q5
	s_cmpk_lt_u32 s25, 0x80
	s_cbranch_scc0 .Lffp_q4b
	s_mov_b32 s98, 0
	s_add_u32 s25, s25, 0x200
	s_branch .Lffp_jh
.Lffp_q4b:
	s_sub_u32 s25, s25, 0x80
	s_and_b32 s98, s25, 1
	s_lshr_b32 s25, s25, 1
	s_add_u32 s25, s25, 0x280
	s_branch .Lffp_jh
.Lffp_q5:
	s_mov_b32 s98, 1
	s_add_u32 s25, s25, 0x200
.Lffp_jh:
	s_mul_i32 s24, s25, 0x5d2
	s_lshr_b32 s24, s24, 16
	s_mul_i32 vcc_lo, s24, 44
	s_sub_u32 s25, s25, vcc_lo
	s_lshl_b32 s24, s24, 1
	s_or_b32 s98, s24, s98
.Lffp_nomap:
	s_mul_i32 s24, s98, 88
	s_add_i32 s24, s24, s25
	s_lshl_b32 s23, s98, 1
	s_lshl_b32 s99, s24, 6
	s_lshl_b32 s25, s25, 6
	s_lshl_b32 s24, s23, 7
	v_lshlrev_b32_e32 v0, 3, v90
	v_ashrrev_i32_e32 v89, 3, v90
	v_and_b32_e32 v88, 56, v0
	s_waitcnt lgkmcnt(0)
	v_lshrrev_b32_e32 v84, 2, v90
	v_lshrrev_b32_e32 v85, 6, v90
	v_lshl_add_u32 v84, v85, 4, v84
	v_bfe_u32 v85, v90, 4, 2
	v_and_b32_e32 v86, 3, v90
	v_xor_b32_e32 v85, v85, v86
	v_lshlrev_b32_e32 v85, 4, v85
	v_add_u32_e32 v86, s24, v84
	v_lshl_or_b32 v66, v86, 11, v85
	v_add_u32_e32 v68, 0x8000, v66
	v_add_u32_e32 v70, 0x40000, v66
	v_add_u32_e32 v72, 0x48000, v66
	s_lshr_b32 vcc_lo, s80, 6
	s_and_b32 vcc_hi, vcc_lo, 1
	s_mul_i32 vcc_hi, vcc_hi, 0xb00
	s_lshr_b32 vcc_lo, vcc_lo, 1
	s_lshl_b32 vcc_lo, vcc_lo, 5
	s_add_i32 vcc_lo, vcc_lo, vcc_hi
	s_add_i32 vcc_lo, vcc_lo, s25
	v_bfe_u32 v86, v90, 2, 4
	v_add_u32_e32 v86, vcc_lo, v86
	v_lshl_or_b32 v74, v86, 11, v85
	v_add_u32_e32 v76, 0x8000, v74
	v_mov_b32_e32 v67, 0
	v_mov_b32_e32 v69, 0
	v_mov_b32_e32 v71, 0
	v_mov_b32_e32 v73, 0
	v_mov_b32_e32 v75, 0
	v_mov_b32_e32 v77, 0
	v_lshl_add_u64 v[66:67], v[66:67], 0, s[72:73]
	v_lshl_add_u64 v[68:69], v[68:69], 0, s[72:73]
	v_lshl_add_u64 v[70:71], v[70:71], 0, s[72:73]
	v_lshl_add_u64 v[72:73], v[72:73], 0, s[72:73]
	v_lshl_add_u64 v[74:75], v[74:75], 0, s[4:5]
	v_lshl_add_u64 v[76:77], v[76:77], 0, s[4:5]
	v_mov_b32_e32 v84, 64
	v_mov_b32_e32 v85, 0
	v_lshl_add_u64 v[126:127], v[66:67], 0, v[84:85]
	v_lshl_add_u64 v[128:129], v[68:69], 0, v[84:85]
	v_lshl_add_u64 v[130:131], v[70:71], 0, v[84:85]
	v_lshl_add_u64 v[132:133], v[72:73], 0, v[84:85]
	v_lshl_add_u64 v[244:245], v[74:75], 0, v[84:85]
	v_lshl_add_u64 v[246:247], v[76:77], 0, v[84:85]
	v_bfe_u32 v84, v90, 5, 1
	v_bfe_u32 v85, v90, 2, 2
	v_xor_b32_e32 v84, v84, v85
	v_lshlrev_b32_e32 v84, 4, v84
	v_lshrrev_b32_e32 v85, 1, v90
	v_and_b32_e32 v85, 64, v85
	v_and_b32_e32 v86, 31, v90
	v_or_b32_e32 v85, v85, v86
	v_lshl_or_b32 v78, v85, 6, v84
	v_xor_b32_e32 v79, 32, v78
	v_and_b32_e32 v85, 0x5f, v90
	v_lshl_or_b32 v80, v85, 6, v84
	v_add_u32_e32 v80, 0x4000, v80
	v_xor_b32_e32 v81, 32, v80
	v_mov_b32_e32 v82, 0x80
	v_mov_b32_e32 v83, 0
	s_lshl_b32 vcc_lo, s80, 5
	v_ashrrev_i32_e32 v2, 1, v90
	v_and_b32_e32 v91, 0xffffffc0, v2
	v_and_b32_e32 v0, 31, v90
	v_mov_b32_e32 v34, 0
	v_mov_b32_e32 v35, 0
	v_mov_b32_e32 v36, 0
	v_mov_b32_e32 v37, 0
	v_mov_b32_e32 v38, 0
	v_mov_b32_e32 v39, 0
	v_mov_b32_e32 v40, 0
	v_mov_b32_e32 v41, 0
	v_mov_b32_e32 v42, 0
	v_mov_b32_e32 v43, 0
	v_mov_b32_e32 v44, 0
	v_mov_b32_e32 v45, 0
	v_mov_b32_e32 v46, 0
	v_mov_b32_e32 v47, 0
	v_mov_b32_e32 v48, 0
	v_mov_b32_e32 v49, 0
	v_mov_b32_e32 v50, 0
	v_mov_b32_e32 v51, 0
	v_mov_b32_e32 v52, 0
	v_mov_b32_e32 v53, 0
	v_mov_b32_e32 v54, 0
	v_mov_b32_e32 v55, 0
	v_mov_b32_e32 v56, 0
	v_mov_b32_e32 v57, 0
	v_mov_b32_e32 v58, 0
	v_mov_b32_e32 v59, 0
	v_mov_b32_e32 v60, 0
	v_mov_b32_e32 v61, 0
	v_mov_b32_e32 v62, 0
	v_mov_b32_e32 v63, 0
	v_mov_b32_e32 v64, 0
	v_mov_b32_e32 v65, 0
	v_mov_b32_e32 v2, 0
	v_mov_b32_e32 v3, 0
	v_mov_b32_e32 v4, 0
	v_mov_b32_e32 v5, 0
	v_mov_b32_e32 v6, 0
	v_mov_b32_e32 v7, 0
	v_mov_b32_e32 v8, 0
	v_mov_b32_e32 v9, 0
	v_mov_b32_e32 v10, 0
	v_mov_b32_e32 v11, 0
	v_mov_b32_e32 v12, 0
	v_mov_b32_e32 v13, 0
	v_mov_b32_e32 v14, 0
	v_mov_b32_e32 v15, 0
	v_mov_b32_e32 v16, 0
	v_mov_b32_e32 v17, 0
	v_mov_b32_e32 v18, 0
	v_mov_b32_e32 v19, 0
	v_mov_b32_e32 v20, 0
	v_mov_b32_e32 v21, 0
	v_mov_b32_e32 v22, 0
	v_mov_b32_e32 v23, 0
	v_mov_b32_e32 v24, 0
	v_mov_b32_e32 v25, 0
	v_mov_b32_e32 v26, 0
	v_mov_b32_e32 v27, 0
	v_mov_b32_e32 v28, 0
	v_mov_b32_e32 v29, 0
	v_mov_b32_e32 v30, 0
	v_mov_b32_e32 v31, 0
	v_mov_b32_e32 v32, 0
	v_mov_b32_e32 v33, 0
	v_mov_b32_e32 v94, 0
	v_mov_b32_e32 v95, 0
	v_mov_b32_e32 v96, 0
	v_mov_b32_e32 v97, 0
	v_mov_b32_e32 v98, 0
	v_mov_b32_e32 v99, 0
	v_mov_b32_e32 v100, 0
	v_mov_b32_e32 v101, 0
	v_mov_b32_e32 v102, 0
	v_mov_b32_e32 v103, 0
	v_mov_b32_e32 v104, 0
	v_mov_b32_e32 v105, 0
	v_mov_b32_e32 v106, 0
	v_mov_b32_e32 v107, 0
	v_mov_b32_e32 v108, 0
	v_mov_b32_e32 v109, 0
	v_mov_b32_e32 v110, 0
	v_mov_b32_e32 v111, 0
	v_mov_b32_e32 v112, 0
	v_mov_b32_e32 v113, 0
	v_mov_b32_e32 v114, 0
	v_mov_b32_e32 v115, 0
	v_mov_b32_e32 v116, 0
	v_mov_b32_e32 v117, 0
	v_mov_b32_e32 v118, 0
	v_mov_b32_e32 v119, 0
	v_mov_b32_e32 v120, 0
	v_mov_b32_e32 v121, 0
	v_mov_b32_e32 v122, 0
	v_mov_b32_e32 v123, 0
	v_mov_b32_e32 v124, 0
	v_mov_b32_e32 v125, 0
	v_mov_b32_e32 v134, 0
	v_mov_b32_e32 v135, 0
	v_mov_b32_e32 v136, 0
	v_mov_b32_e32 v137, 0
	v_mov_b32_e32 v138, 0
	v_mov_b32_e32 v139, 0
	v_mov_b32_e32 v140, 0
	v_mov_b32_e32 v141, 0
	v_mov_b32_e32 v142, 0
	v_mov_b32_e32 v143, 0
	v_mov_b32_e32 v144, 0
	v_mov_b32_e32 v145, 0
	v_mov_b32_e32 v146, 0
	v_mov_b32_e32 v147, 0
	v_mov_b32_e32 v148, 0
	v_mov_b32_e32 v149, 0
	v_mov_b32_e32 v150, 0
	v_mov_b32_e32 v151, 0
	v_mov_b32_e32 v152, 0
	v_mov_b32_e32 v153, 0
	v_mov_b32_e32 v154, 0
	v_mov_b32_e32 v155, 0
	v_mov_b32_e32 v156, 0
	v_mov_b32_e32 v157, 0
	v_mov_b32_e32 v158, 0
	v_mov_b32_e32 v159, 0
	v_mov_b32_e32 v160, 0
	v_mov_b32_e32 v161, 0
	v_mov_b32_e32 v162, 0
	v_mov_b32_e32 v163, 0
	v_mov_b32_e32 v164, 0
	v_mov_b32_e32 v165, 0
	s_barrier
	s_mov_b32 m0, vcc_lo
	s_nop 0
	global_load_lds_dwordx4 v[66:67], off
	s_add_u32 m0, vcc_lo, 0x6000
	s_nop 0
	global_load_lds_dwordx4 v[126:127], off
	s_add_u32 m0, vcc_lo, 0x400
	s_nop 0
	global_load_lds_dwordx4 v[68:69], off
	s_add_u32 m0, vcc_lo, 0x6400
	s_nop 0
	global_load_lds_dwordx4 v[128:129], off
	s_add_u32 m0, vcc_lo, 0x2000
	s_nop 0
	global_load_lds_dwordx4 v[70:71], off
	s_add_u32 m0, vcc_lo, 0x8000
	s_nop 0
	global_load_lds_dwordx4 v[130:131], off
	s_add_u32 m0, vcc_lo, 0x2400
	s_nop 0
	global_load_lds_dwordx4 v[72:73], off
	s_add_u32 m0, vcc_lo, 0x8400
	s_nop 0
	global_load_lds_dwordx4 v[132:133], off
	s_add_u32 m0, vcc_lo, 0x4000
	s_nop 0
	global_load_lds_dwordx4 v[74:75], off
	s_add_u32 m0, vcc_lo, 0xa000
	s_nop 0
	global_load_lds_dwordx4 v[244:245], off
	s_add_u32 m0, vcc_lo, 0x4400
	s_nop 0
	global_load_lds_dwordx4 v[76:77], off
	s_add_u32 m0, vcc_lo, 0xa400
	s_nop 0
	global_load_lds_dwordx4 v[246:247], off
	v_lshl_add_u64 v[66:67], v[66:67], 0, v[82:83]
	v_lshl_add_u64 v[68:69], v[68:69], 0, v[82:83]
	v_lshl_add_u64 v[70:71], v[70:71], 0, v[82:83]
	v_lshl_add_u64 v[72:73], v[72:73], 0, v[82:83]
	v_lshl_add_u64 v[74:75], v[74:75], 0, v[82:83]
	v_lshl_add_u64 v[76:77], v[76:77], 0, v[82:83]
	v_lshl_add_u64 v[126:127], v[126:127], 0, v[82:83]
	v_lshl_add_u64 v[128:129], v[128:129], 0, v[82:83]
	v_lshl_add_u64 v[130:131], v[130:131], 0, v[82:83]
	v_lshl_add_u64 v[132:133], v[132:133], 0, v[82:83]
	v_lshl_add_u64 v[244:245], v[244:245], 0, v[82:83]
	v_lshl_add_u64 v[246:247], v[246:247], 0, v[82:83]
	s_waitcnt vmcnt(0)
	s_barrier
	ds_read_b128 v[166:169], v78
	ds_read_b128 v[170:173], v80
	ds_read_b128 v[174:177], v80 offset:2048
	ds_read_b128 v[178:181], v78 offset:2048
	ds_read_b128 v[182:185], v78 offset:8192
	ds_read_b128 v[188:191], v78 offset:10240
	s_waitcnt lgkmcnt(4)
	v_mfma_f32_32x32x16_bf16 v[34:49], v[166:169], v[170:173], v[34:49]
	ds_read_b128 v[192:195], v79
	s_waitcnt lgkmcnt(4)
	v_mfma_f32_32x32x16_bf16 v[50:65], v[166:169], v[174:177], v[50:65]
	ds_read_b128 v[206:209], v81
	s_waitcnt lgkmcnt(4)
	v_mfma_f32_32x32x16_bf16 v[2:17], v[178:181], v[170:173], v[2:17]
	ds_read_b128 v[210:213], v81 offset:2048
	v_mfma_f32_32x32x16_bf16 v[18:33], v[178:181], v[174:177], v[18:33]
	ds_read_b128 v[222:225], v79 offset:2048
	s_waitcnt lgkmcnt(5)
	v_mfma_f32_32x32x16_bf16 v[94:109], v[182:185], v[170:173], v[94:109]
	ds_read_b128 v[236:239], v79 offset:8192
	v_mfma_f32_32x32x16_bf16 v[110:125], v[182:185], v[174:177], v[110:125]
	ds_read_b128 v[240:243], v79 offset:10240
	s_waitcnt lgkmcnt(6)
	v_mfma_f32_32x32x16_bf16 v[134:149], v[188:191], v[170:173], v[134:149]
	v_mfma_f32_32x32x16_bf16 v[150:165], v[188:191], v[174:177], v[150:165]
	s_waitcnt vmcnt(0) lgkmcnt(0)
	s_barrier
	s_mov_b32 vcc_hi, 4
